# gemm_in/gemm_out: epilogue stores no longer drained before the end-of-tile barrier (next tile's first loads overlap the drain)
# baseline (speedup 1.0000x reference)
.LBB0_453:
	s_or_b64 exec, exec, s[10:11]
	s_barrier

.LBB0_1165:
	s_or_b64 exec, exec, s[0:1]
	v_mov_b32_e32 v129, v167
	v_readlane_b32 s0, v254, 1
	v_ashrrev_i32_e32 v128, 2, v129
	v_and_b32_e32 v130, 15, v129
	v_and_b32_e32 v128, 0xffffffc0, v128
	v_lshrrev_b32_e32 v131, 2, v129
	v_lshrrev_b32_e32 v129, 1, v129
	v_add_u32_e32 v128, s36, v128
	v_and_b32_e32 v129, 0x60, v129
	v_and_or_b32 v128, v131, 12, v128
	v_or3_b32 v130, v130, v129, s34
	v_ashrrev_i32_e32 v131, 31, v130
	v_ashrrev_i32_e32 v129, 31, v128
	v_or_b32_e32 v134, 1, v128
	v_lshl_add_u64 v[130:131], v[130:131], 2, s[26:27]
	v_lshlrev_b64 v[132:133], 13, v[128:129]
	v_ashrrev_i32_e32 v135, 31, v134
	v_lshl_add_u64 v[132:133], v[130:131], 0, v[132:133]
	v_lshlrev_b64 v[134:135], 13, v[134:135]
	global_store_dword v[132:133], v124, off
	v_lshl_add_u64 v[134:135], v[130:131], 0, v[134:135]
	v_or_b32_e32 v124, 2, v128
	v_or_b32_e32 v136, 3, v128
	global_store_dword v[134:135], v125, off
	v_ashrrev_i32_e32 v125, 31, v124
	v_ashrrev_i32_e32 v137, 31, v136
	v_lshlrev_b64 v[124:125], 13, v[124:125]
	v_lshlrev_b64 v[136:137], 13, v[136:137]
	v_lshl_add_u64 v[124:125], v[130:131], 0, v[124:125]
	v_lshl_add_u64 v[136:137], v[130:131], 0, v[136:137]
	global_store_dword v[124:125], v126, off
	global_store_dword v[136:137], v127, off
	global_store_dword v[132:133], v120, off offset:64
	global_store_dword v[134:135], v121, off offset:64
	global_store_dword v[124:125], v122, off offset:64
	global_store_dword v[136:137], v123, off offset:64
	v_or_b32_e32 v120, 16, v128
	v_ashrrev_i32_e32 v121, 31, v120
	v_or_b32_e32 v122, 17, v128
	v_lshlrev_b64 v[120:121], 13, v[120:121]
	v_ashrrev_i32_e32 v123, 31, v122
	v_lshl_add_u64 v[120:121], v[130:131], 0, v[120:121]
	v_lshlrev_b64 v[122:123], 13, v[122:123]
	global_store_dword v[120:121], v116, off
	v_lshl_add_u64 v[122:123], v[130:131], 0, v[122:123]
	v_or_b32_e32 v116, 18, v128
	v_or_b32_e32 v126, 19, v128
	global_store_dword v[122:123], v117, off
	v_ashrrev_i32_e32 v117, 31, v116
	v_ashrrev_i32_e32 v127, 31, v126
	v_lshlrev_b64 v[116:117], 13, v[116:117]
	v_lshlrev_b64 v[126:127], 13, v[126:127]
	v_lshl_add_u64 v[116:117], v[130:131], 0, v[116:117]
	v_lshl_add_u64 v[126:127], v[130:131], 0, v[126:127]
	global_store_dword v[116:117], v118, off
	global_store_dword v[126:127], v119, off
	global_store_dword v[120:121], v112, off offset:64
	global_store_dword v[122:123], v113, off offset:64
	global_store_dword v[116:117], v114, off offset:64
	global_store_dword v[126:127], v115, off offset:64
	v_or_b32_e32 v112, 32, v128
	v_ashrrev_i32_e32 v113, 31, v112
	v_or_b32_e32 v114, 33, v128
	v_lshlrev_b64 v[112:113], 13, v[112:113]
	v_ashrrev_i32_e32 v115, 31, v114
	v_lshl_add_u64 v[112:113], v[130:131], 0, v[112:113]
	v_lshlrev_b64 v[114:115], 13, v[114:115]
	global_store_dword v[112:113], v108, off
	v_lshl_add_u64 v[114:115], v[130:131], 0, v[114:115]
	v_or_b32_e32 v108, 34, v128
	v_or_b32_e32 v118, 35, v128
	global_store_dword v[114:115], v109, off
	v_ashrrev_i32_e32 v109, 31, v108
	v_ashrrev_i32_e32 v119, 31, v118
	v_lshlrev_b64 v[108:109], 13, v[108:109]
	v_lshlrev_b64 v[118:119], 13, v[118:119]
	v_lshl_add_u64 v[108:109], v[130:131], 0, v[108:109]
	v_lshl_add_u64 v[118:119], v[130:131], 0, v[118:119]
	global_store_dword v[108:109], v110, off
	global_store_dword v[118:119], v111, off
	global_store_dword v[112:113], v104, off offset:64
	global_store_dword v[114:115], v105, off offset:64
	global_store_dword v[108:109], v106, off offset:64
	global_store_dword v[118:119], v107, off offset:64
	v_or_b32_e32 v104, 48, v128
	v_ashrrev_i32_e32 v105, 31, v104
	v_or_b32_e32 v106, 49, v128
	v_lshlrev_b64 v[104:105], 13, v[104:105]
	v_ashrrev_i32_e32 v107, 31, v106
	v_lshl_add_u64 v[104:105], v[130:131], 0, v[104:105]
	v_lshlrev_b64 v[106:107], 13, v[106:107]
	global_store_dword v[104:105], v84, off
	v_lshl_add_u64 v[106:107], v[130:131], 0, v[106:107]
	v_or_b32_e32 v84, 50, v128
	v_or_b32_e32 v110, 51, v128
	global_store_dword v[106:107], v85, off
	v_ashrrev_i32_e32 v85, 31, v84
	v_ashrrev_i32_e32 v111, 31, v110
	v_lshlrev_b64 v[84:85], 13, v[84:85]
	v_lshlrev_b64 v[110:111], 13, v[110:111]
	v_lshl_add_u64 v[84:85], v[130:131], 0, v[84:85]
	v_lshl_add_u64 v[110:111], v[130:131], 0, v[110:111]
	global_store_dword v[84:85], v86, off
	global_store_dword v[110:111], v87, off
	global_store_dword v[104:105], v76, off offset:64
	global_store_dword v[106:107], v77, off offset:64
	global_store_dword v[84:85], v78, off offset:64
	global_store_dword v[110:111], v79, off offset:64
	global_store_dword v[132:133], v100, off offset:512
	global_store_dword v[134:135], v101, off offset:512
	global_store_dword v[124:125], v102, off offset:512
	global_store_dword v[136:137], v103, off offset:512
	global_store_dword v[132:133], v96, off offset:576
	global_store_dword v[134:135], v97, off offset:576
	global_store_dword v[124:125], v98, off offset:576
	global_store_dword v[136:137], v99, off offset:576
	global_store_dword v[120:121], v92, off offset:512
	global_store_dword v[122:123], v93, off offset:512
	global_store_dword v[116:117], v94, off offset:512
	global_store_dword v[126:127], v95, off offset:512
	global_store_dword v[120:121], v88, off offset:576
	global_store_dword v[122:123], v89, off offset:576
	global_store_dword v[116:117], v90, off offset:576
	global_store_dword v[126:127], v91, off offset:576
	global_store_dword v[112:113], v80, off offset:512
	global_store_dword v[114:115], v81, off offset:512
	global_store_dword v[108:109], v82, off offset:512
	global_store_dword v[118:119], v83, off offset:512
	global_store_dword v[112:113], v72, off offset:576
	global_store_dword v[114:115], v73, off offset:576
	global_store_dword v[108:109], v74, off offset:576
	global_store_dword v[118:119], v75, off offset:576
	global_store_dword v[104:105], v68, off offset:512
	global_store_dword v[106:107], v69, off offset:512
	global_store_dword v[84:85], v70, off offset:512
	global_store_dword v[110:111], v71, off offset:512
	global_store_dword v[104:105], v64, off offset:576
	global_store_dword v[106:107], v65, off offset:576
	global_store_dword v[84:85], v66, off offset:576
	global_store_dword v[110:111], v67, off offset:576
	v_add_u32_e32 v64, 0x80, v128
	v_ashrrev_i32_e32 v65, 31, v64
	v_add_u32_e32 v66, 0x81, v128
	v_lshlrev_b64 v[64:65], 13, v[64:65]
	v_ashrrev_i32_e32 v67, 31, v66
	v_lshl_add_u64 v[64:65], v[130:131], 0, v[64:65]
	v_lshlrev_b64 v[66:67], 13, v[66:67]
	global_store_dword v[64:65], v60, off
	v_lshl_add_u64 v[66:67], v[130:131], 0, v[66:67]
	v_add_u32_e32 v60, 0x82, v128
	v_add_u32_e32 v68, 0x83, v128
	global_store_dword v[66:67], v61, off
	v_ashrrev_i32_e32 v61, 31, v60
	v_ashrrev_i32_e32 v69, 31, v68
	v_lshlrev_b64 v[60:61], 13, v[60:61]
	v_lshlrev_b64 v[68:69], 13, v[68:69]
	v_lshl_add_u64 v[60:61], v[130:131], 0, v[60:61]
	v_lshl_add_u64 v[68:69], v[130:131], 0, v[68:69]
	global_store_dword v[60:61], v62, off
	global_store_dword v[68:69], v63, off
	global_store_dword v[64:65], v56, off offset:64
	global_store_dword v[66:67], v57, off offset:64
	global_store_dword v[60:61], v58, off offset:64
	global_store_dword v[68:69], v59, off offset:64
	v_add_u32_e32 v56, 0x90, v128
	v_ashrrev_i32_e32 v57, 31, v56
	v_add_u32_e32 v58, 0x91, v128
	v_lshlrev_b64 v[56:57], 13, v[56:57]
	v_ashrrev_i32_e32 v59, 31, v58
	v_lshl_add_u64 v[56:57], v[130:131], 0, v[56:57]
	v_lshlrev_b64 v[58:59], 13, v[58:59]
	global_store_dword v[56:57], v52, off
	v_lshl_add_u64 v[58:59], v[130:131], 0, v[58:59]
	v_add_u32_e32 v52, 0x92, v128
	v_add_u32_e32 v62, 0x93, v128
	global_store_dword v[58:59], v53, off
	v_ashrrev_i32_e32 v53, 31, v52
	v_ashrrev_i32_e32 v63, 31, v62
	v_lshlrev_b64 v[52:53], 13, v[52:53]
	v_lshlrev_b64 v[62:63], 13, v[62:63]
	v_lshl_add_u64 v[52:53], v[130:131], 0, v[52:53]
	v_lshl_add_u64 v[62:63], v[130:131], 0, v[62:63]
	global_store_dword v[52:53], v54, off
	global_store_dword v[62:63], v55, off
	global_store_dword v[56:57], v48, off offset:64
	global_store_dword v[58:59], v49, off offset:64
	global_store_dword v[52:53], v50, off offset:64
	global_store_dword v[62:63], v51, off offset:64
	v_add_u32_e32 v48, 0xa0, v128
	v_ashrrev_i32_e32 v49, 31, v48
	v_add_u32_e32 v50, 0xa1, v128
	v_lshlrev_b64 v[48:49], 13, v[48:49]
	v_ashrrev_i32_e32 v51, 31, v50
	v_lshl_add_u64 v[48:49], v[130:131], 0, v[48:49]
	v_lshlrev_b64 v[50:51], 13, v[50:51]
	global_store_dword v[48:49], v44, off
	v_lshl_add_u64 v[50:51], v[130:131], 0, v[50:51]
	v_add_u32_e32 v44, 0xa2, v128
	v_add_u32_e32 v54, 0xa3, v128
	global_store_dword v[50:51], v45, off
	v_ashrrev_i32_e32 v45, 31, v44
	v_ashrrev_i32_e32 v55, 31, v54
	v_lshlrev_b64 v[44:45], 13, v[44:45]
	v_lshlrev_b64 v[54:55], 13, v[54:55]
	v_lshl_add_u64 v[44:45], v[130:131], 0, v[44:45]
	v_lshl_add_u64 v[54:55], v[130:131], 0, v[54:55]
	global_store_dword v[44:45], v46, off
	global_store_dword v[54:55], v47, off
	global_store_dword v[48:49], v40, off offset:64
	global_store_dword v[50:51], v41, off offset:64
	global_store_dword v[44:45], v42, off offset:64
	global_store_dword v[54:55], v43, off offset:64
	v_add_u32_e32 v40, 0xb0, v128
	v_ashrrev_i32_e32 v41, 31, v40
	v_add_u32_e32 v42, 0xb1, v128
	v_lshlrev_b64 v[40:41], 13, v[40:41]
	v_ashrrev_i32_e32 v43, 31, v42
	v_lshl_add_u64 v[40:41], v[130:131], 0, v[40:41]
	v_lshlrev_b64 v[42:43], 13, v[42:43]
	global_store_dword v[40:41], v36, off
	v_lshl_add_u64 v[42:43], v[130:131], 0, v[42:43]
	v_add_u32_e32 v36, 0xb2, v128
	v_add_u32_e32 v46, 0xb3, v128
	global_store_dword v[42:43], v37, off
	v_ashrrev_i32_e32 v37, 31, v36
	v_ashrrev_i32_e32 v47, 31, v46
	v_lshlrev_b64 v[36:37], 13, v[36:37]
	v_lshlrev_b64 v[46:47], 13, v[46:47]
	s_add_i32 s44, s44, s0
	v_lshl_add_u64 v[36:37], v[130:131], 0, v[36:37]
	v_lshl_add_u64 v[46:47], v[130:131], 0, v[46:47]
	s_cmp_ge_i32 s44, s46
	global_store_dword v[36:37], v38, off
	global_store_dword v[46:47], v39, off
	global_store_dword v[40:41], v28, off offset:64
	global_store_dword v[42:43], v29, off offset:64
	global_store_dword v[36:37], v30, off offset:64
	global_store_dword v[46:47], v31, off offset:64
	global_store_dword v[64:65], v32, off offset:512
	global_store_dword v[66:67], v33, off offset:512
	global_store_dword v[60:61], v34, off offset:512
	global_store_dword v[68:69], v35, off offset:512
	global_store_dword v[64:65], v24, off offset:576
	global_store_dword v[66:67], v25, off offset:576
	global_store_dword v[60:61], v26, off offset:576
	global_store_dword v[68:69], v27, off offset:576
	global_store_dword v[56:57], v20, off offset:512
	global_store_dword v[58:59], v21, off offset:512
	global_store_dword v[52:53], v22, off offset:512
	global_store_dword v[62:63], v23, off offset:512
	global_store_dword v[56:57], v16, off offset:576
	global_store_dword v[58:59], v17, off offset:576
	global_store_dword v[52:53], v18, off offset:576
	global_store_dword v[62:63], v19, off offset:576
	global_store_dword v[48:49], v12, off offset:512
	global_store_dword v[50:51], v13, off offset:512
	global_store_dword v[44:45], v14, off offset:512
	global_store_dword v[54:55], v15, off offset:512
	global_store_dword v[48:49], v8, off offset:576
	global_store_dword v[50:51], v9, off offset:576
	global_store_dword v[44:45], v10, off offset:576
	global_store_dword v[54:55], v11, off offset:576
	global_store_dword v[40:41], v4, off offset:512
	global_store_dword v[42:43], v5, off offset:512
	global_store_dword v[36:37], v6, off offset:512
	global_store_dword v[46:47], v7, off offset:512
	global_store_dword v[40:41], v0, off offset:576
	global_store_dword v[42:43], v1, off offset:576
	global_store_dword v[36:37], v2, off offset:576
	global_store_dword v[46:47], v3, off offset:576
	s_barrier
	v_readlane_b32 s1, v254, 2
	s_cbranch_scc1 .LBB0_1172
